# split-phase P2->P3 seam v2: all workgroups watch the cross-XCC generation word at this seam, so XCC leaders that run a late in-projection unit skip the wait too
# speedup vs baseline: 1.0028x; 1.0028x over previous
; __device__ __forceinline__ unsigned xb_ld(unsigned* p)              { return __hip_atomic_load(p, __ATOMIC_RELAXED, __HIP_MEMORY_SCOPE_AGENT); }
; __device__ __forceinline__ unsigned xb_add(unsigned* p, unsigned v) { return __hip_atomic_fetch_add(p, v, __ATOMIC_RELAXED, __HIP_MEMORY_SCOPE_AGENT); }
; #define XB_SPIN(cond, bar) do { unsigned _sp = 0; while (cond) { __builtin_amdgcn_s_sleep(1); \
;     if ((++_sp & 255u) == 0u) { if (xb_ld(&(bar)[XB_TMO])) break; if (_sp > XB_SPIN_CAP) { atomicAdd(&(bar)[XB_TMO], 1u); break; } } } } while (0)
; __device__ __forceinline__ void xcd_barrier(const XcdBarrier& b) {
;     ...
;         const unsigned old = xb_add(&bar[XB_XSUB(b.x)], 1u);
;         const unsigned gen = old / nloc;
;         if (old + 1u == (gen + 1u) * nloc) {
;             __builtin_amdgcn_fence(__ATOMIC_RELEASE, "agent");
;             asm volatile("s_waitcnt vmcnt(0)" ::: "memory");
;             const unsigned og = xb_add(&bar[XB_TOP], 1u);
;             const unsigned tg = og / nx;
;             if (og + 1u == (tg + 1u) * nx) xb_add(&bar[XB_TOPGEN], 1u);
;             else XB_SPIN(xb_ld(&bar[XB_TOPGEN]) == tg, bar);
;             __builtin_amdgcn_fence(__ATOMIC_ACQUIRE, "agent");
;             xb_add(&bar[XB_XGEN(b.x)], 1u);
;             asm volatile("s_waitcnt vmcnt(0)" ::: "memory");
;         } else {
;             XB_SPIN(xb_ld(&bar[XB_XGEN(b.x)]) == gen, bar);
.LBB0_302:
	s_or_b64 exec, exec, s[38:39]
	v_cvt_f32_u32_e32 v5, v3
	s_waitcnt vmcnt(0)
	v_readfirstlane_b32 s12, v4
	v_sub_u32_e32 v4, 0, v3
	v_rcp_iflag_f32_e32 v5, v5
	v_add_u32_e32 v6, s12, v0
	v_mul_f32_e32 v5, 0x4f7ffffe, v5
	v_cvt_u32_f32_e32 v5, v5
	v_mul_lo_u32 v0, v4, v5
	v_mul_hi_u32 v0, v5, v0
	v_add_u32_e32 v0, v5, v0
	v_mul_hi_u32 v0, v6, v0
	v_mul_lo_u32 v4, v0, v3
	v_sub_u32_e32 v4, v6, v4
	v_add_u32_e32 v5, 1, v0
	v_cmp_ge_u32_e32 vcc, v4, v3
	s_nop 1
	v_cndmask_b32_e32 v0, v0, v5, vcc
	v_sub_u32_e32 v5, v4, v3
	v_cndmask_b32_e32 v4, v4, v5, vcc
	v_add_u32_e32 v5, 1, v0
	v_cmp_ge_u32_e32 vcc, v4, v3
	v_add_u32_e32 v4, 1, v6
	s_nop 0
	v_cndmask_b32_e32 v0, v0, v5, vcc
	v_mul_lo_u32 v5, v3, v0
	v_add_u32_e32 v3, v5, v3
	v_cmp_ne_u32_e32 vcc, v4, v3
	s_mov_b32 s13, -1
	s_nop 0
	v_writelane_b32 v255, s13, 47
	s_and_saveexec_b64 s[12:13], vcc
	s_xor_b64 s[38:39], exec, s[12:13]
	s_cbranch_execz .LBB0_316
	buffer_inv sc1
	v_readlane_b32 s12, v255, 14
	v_readlane_b32 s13, v255, 15
	s_waitcnt lgkmcnt(0)
	s_nop 3
	global_load_dword v2, v1, s[12:13] sc1
	s_waitcnt vmcnt(0)
	v_cmp_eq_u32_e32 vcc, v2, v0
	v_readlane_b32 s26, v255, 31
	s_movk_i32 s27, 0x80
	s_cmp_lt_u32 s26, s27
	s_cbranch_scc0 .Lss_nodefer
	v_readfirstlane_b32 s27, v0
	s_nop 1
	v_writelane_b32 v255, s27, 47
	s_mov_b64 vcc, 0

; __device__ __forceinline__ unsigned xb_ld(unsigned* p)              { return __hip_atomic_load(p, __ATOMIC_RELAXED, __HIP_MEMORY_SCOPE_AGENT); }
; __device__ __forceinline__ unsigned xb_add(unsigned* p, unsigned v) { return __hip_atomic_fetch_add(p, v, __ATOMIC_RELAXED, __HIP_MEMORY_SCOPE_AGENT); }
; #define XB_SPIN(cond, bar) do { unsigned _sp = 0; while (cond) { __builtin_amdgcn_s_sleep(1); \
;     if ((++_sp & 255u) == 0u) { if (xb_ld(&(bar)[XB_TMO])) break; if (_sp > XB_SPIN_CAP) { atomicAdd(&(bar)[XB_TMO], 1u); break; } } } } while (0)
; __device__ __forceinline__ void xcd_barrier(const XcdBarrier& b) {
;     ...
;             const unsigned og = xb_add(&bar[XB_TOP], 1u);
;             const unsigned tg = og / nx;
;             if (og + 1u == (tg + 1u) * nx) xb_add(&bar[XB_TOPGEN], 1u);
;             else XB_SPIN(xb_ld(&bar[XB_TOPGEN]) == tg, bar);
.LBB0_319:
	s_or_b64 exec, exec, s[40:41]
	s_waitcnt vmcnt(0)
	v_readfirstlane_b32 s12, v3
	v_sub_u32_e32 v4, 0, v2
	s_mov_b64 s[40:41], -1
	v_add_u32_e32 v3, s12, v0
	v_cvt_f32_u32_e32 v0, v2
	v_readlane_b32 s12, v255, 14
	v_readlane_b32 s13, v255, 15
	v_rcp_iflag_f32_e32 v0, v0
	s_nop 0
	v_mul_f32_e32 v0, 0x4f7ffffe, v0
	v_cvt_u32_f32_e32 v0, v0
	v_mul_lo_u32 v4, v4, v0
	v_mul_hi_u32 v4, v0, v4
	v_add_u32_e32 v0, v0, v4
	v_mul_hi_u32 v0, v3, v0
	v_mul_lo_u32 v4, v0, v2
	v_sub_u32_e32 v4, v3, v4
	v_cmp_ge_u32_e32 vcc, v4, v2
	v_add_u32_e32 v5, 1, v0
	v_add_u32_e32 v3, 1, v3
	v_cndmask_b32_e32 v0, v0, v5, vcc
	v_sub_u32_e32 v5, v4, v2
	v_cndmask_b32_e32 v4, v4, v5, vcc
	v_cmp_ge_u32_e32 vcc, v4, v2
	v_add_u32_e32 v4, 1, v0
	s_nop 0
	v_cndmask_b32_e32 v0, v0, v4, vcc
	v_mul_lo_u32 v4, v2, v0
	v_add_u32_e32 v2, v4, v2
	v_cmp_ne_u32_e32 vcc, v3, v2
	v_mov_b64_e32 v[2:3], s[12:13]
	s_and_saveexec_b64 s[38:39], vcc
	s_cbranch_execz .LBB0_331
	v_readlane_b32 s12, v255, 14
	v_readlane_b32 s13, v255, 15
	s_mov_b64 s[42:43], 0
	s_nop 3
	global_load_dword v2, v1, s[12:13] sc1
	s_waitcnt vmcnt(0)
	v_cmp_eq_u32_e32 vcc, v2, v0
	v_readlane_b32 s26, v255, 31
	s_movk_i32 s27, 0x80
	s_cmp_lt_u32 s26, s27
	s_cbranch_scc0 .Lss_nodefer_l
	v_readfirstlane_b32 s27, v0
	s_nop 1
	v_writelane_b32 v255, s27, 47
	s_mov_b64 vcc, 0
.Lss_nodefer_l:
	s_and_saveexec_b64 s[40:41], vcc
	s_cbranch_execz .LBB0_330
	s_mov_b32 s12, 1
	s_branch .LBB0_323

; #define PG8_WAIT_V(n) asm volatile("s_waitcnt vmcnt(" #n ")" ::: "memory")
; #define PG8_BAR __builtin_amdgcn_s_barrier()
; __device__ __forceinline__ unsigned xb_ld(unsigned* p)              { return __hip_atomic_load(p, __ATOMIC_RELAXED, __HIP_MEMORY_SCOPE_AGENT); }
; #define XB_SPIN(cond, bar) do { unsigned _sp = 0; while (cond) { __builtin_amdgcn_s_sleep(1); \
;     if ((++_sp & 255u) == 0u) { if (xb_ld(&(bar)[XB_TMO])) break; if (_sp > XB_SPIN_CAP) { atomicAdd(&(bar)[XB_TMO], 1u); break; } } } } while (0)
; template <class Epi, class Sched, bool ALIGN_EPI>
; __device__ __forceinline__ void gemm_phase(PG8_LAS unsigned char* lds, const Gemm g, const Sched& S, const Epi& E) {
;     ...
;     PG8_WAIT_V(0);
;     if constexpr (!ALIGN_EPI) { if (wr == 0) PG8_BAR; }
;     PG8_BAR;
; __device__ __forceinline__ void xcd_barrier(const XcdBarrier& b) {
;     ...
;             XB_SPIN(xb_ld(&bar[XB_XGEN(b.x)]) == gen, bar);
;             __builtin_amdgcn_fence(__ATOMIC_ACQUIRE, "agent");
;             asm volatile("s_waitcnt vmcnt(0)" ::: "memory");
.LBB0_367:
	s_waitcnt vmcnt(0)
	v_readlane_b32 s70, v255, 31
	v_readlane_b32 s94, v255, 32
	v_readlane_b32 s67, v255, 34
	v_readlane_b32 s71, v255, 35
	s_movk_i32 s97, 0x2000
	s_movk_i32 s93, 0x6000
	s_mov_b32 s96, 0xa000
	s_barrier
	v_readlane_b32 s95, v255, 33
	v_readlane_b32 s12, v255, 14
	v_readlane_b32 s13, v255, 15
	v_readlane_b32 s9, v255, 47
	s_mov_b64 s[26:27], exec
	v_cmp_eq_u32_e32 vcc, 0, v147
	s_mov_b32 s6, 0
	s_nop 1
	s_and_b64 exec, exec, vcc
	s_cbranch_execz .Lss_done
